# T21 slot: waves 0-3 run the T21 MFMA chain redundantly and each writes a quarter of its scaled bf16 rows (was wave 0 alone)
# baseline (speedup 1.0000x reference)
.LBB0_236:
	v_lshlrev_b32_e32 v88, 3, v95
	s_cmp_lt_u32 s48, 4
	v_or_b32_e32 v89, 16, v88
	s_waitcnt lgkmcnt(0)
	s_barrier
	s_cbranch_scc1 .LBB0_245
	s_cmp_gt_u32 s48, 3
	s_cbranch_scc0 .Lem_skip
	s_add_i32 s6, s48, -4
	v_lshlrev_b32_e32 v2, 9, v94
	v_lshlrev_b32_e32 v3, 2, v94
	v_lshlrev_b32_e32 v4, 11, v95
	v_lshlrev_b32_e32 v8, 4, v95
	s_lshl_b32 s7, s6, 6
	v_lshl_add_u32 v2, v95, 4, v2
	v_add_u32_e32 v3, 0x24b00, v3
	v_lshl_add_u32 v4, v94, 2, v4
	v_add_u32_e32 v8, s7, v8
	v_add_u32_e32 v2, s7, v2
	s_lshl_b32 s7, s6, 13
	s_add_i32 s7, s7, 0x8000
	v_add_u32_e32 v8, 0x24c00, v8
	v_add_u32_e32 v4, s7, v4
	s_lshl_b32 s7, s6, 10
	s_add_i32 s7, s7, s51
	v_add_u32_e32 v5, 0x80, v4
	v_lshl_add_u32 v9, v93, 4, s7
	ds_read_b32 v182, v3
	ds_read_b32 v184, v3 offset:128
	ds_read_b128 v[150:153], v2
	ds_read_b128 v[154:157], v2 offset:32
	ds_read_b128 v[158:161], v2 offset:256
	ds_read_b128 v[162:165], v2 offset:288
	ds_read_b128 v[166:169], v2 offset:16384
	ds_read_b128 v[170:173], v2 offset:16416
	ds_read_b128 v[174:177], v2 offset:16640
	ds_read_b128 v[178:181], v2 offset:16672
	ds_read_b128 v[186:189], v8
	ds_read_b128 v[190:193], v8 offset:32
	s_waitcnt lgkmcnt(2)
	ds_read2st64_b32 v[194:195], v4 offset1:2
	ds_read2st64_b32 v[196:197], v4 offset0:4 offset1:6
	ds_read2st64_b32 v[198:199], v4 offset0:16 offset1:18
	ds_read2st64_b32 v[200:201], v4 offset0:20 offset1:22
	ds_read2st64_b32 v[202:203], v5 offset1:2
	ds_read2st64_b32 v[204:205], v5 offset0:4 offset1:6
	ds_read2st64_b32 v[206:207], v5 offset0:16 offset1:18
	ds_read2st64_b32 v[208:209], v5 offset0:20 offset1:22
	v_pk_mul_f32 v[150:151], v[150:151], v[182:183] op_sel_hi:[1,0]
	v_pk_mul_f32 v[152:153], v[152:153], v[182:183] op_sel_hi:[1,0]
	v_pk_mul_f32 v[154:155], v[154:155], v[182:183] op_sel_hi:[1,0]
	v_pk_mul_f32 v[156:157], v[156:157], v[182:183] op_sel_hi:[1,0]
	v_cvt_pk_bf16_f32 v10, v150, v151
	v_cvt_pk_bf16_f32 v11, v152, v153
	v_cvt_pk_bf16_f32 v12, v154, v155
	v_cvt_pk_bf16_f32 v13, v156, v157
	v_add_u32_e32 v6, 0x4000, v9
	buffer_store_dwordx4 v[10:13], v6, s[72:75], 0 offen sc1
	v_pk_mul_f32 v[158:159], v[158:159], v[182:183] op_sel_hi:[1,0]
	v_pk_mul_f32 v[160:161], v[160:161], v[182:183] op_sel_hi:[1,0]
	v_pk_mul_f32 v[162:163], v[162:163], v[182:183] op_sel_hi:[1,0]
	v_pk_mul_f32 v[164:165], v[164:165], v[182:183] op_sel_hi:[1,0]
	v_cvt_pk_bf16_f32 v14, v158, v159
	v_cvt_pk_bf16_f32 v15, v160, v161
	v_cvt_pk_bf16_f32 v16, v162, v163
	v_cvt_pk_bf16_f32 v17, v164, v165
	v_add_u32_e32 v7, 0x5000, v9
	buffer_store_dwordx4 v[14:17], v7, s[72:75], 0 offen sc1
	v_pk_mul_f32 v[166:167], v[166:167], v[184:185] op_sel_hi:[1,0]
	v_pk_mul_f32 v[168:169], v[168:169], v[184:185] op_sel_hi:[1,0]
	v_pk_mul_f32 v[170:171], v[170:171], v[184:185] op_sel_hi:[1,0]
	v_pk_mul_f32 v[172:173], v[172:173], v[184:185] op_sel_hi:[1,0]
	v_cvt_pk_bf16_f32 v18, v166, v167
	v_cvt_pk_bf16_f32 v19, v168, v169
	v_cvt_pk_bf16_f32 v20, v170, v171
	v_cvt_pk_bf16_f32 v21, v172, v173
	v_add_u32_e32 v6, 0x6000, v9
	buffer_store_dwordx4 v[18:21], v6, s[72:75], 0 offen sc1
	v_pk_mul_f32 v[174:175], v[174:175], v[184:185] op_sel_hi:[1,0]
	v_pk_mul_f32 v[176:177], v[176:177], v[184:185] op_sel_hi:[1,0]
	v_pk_mul_f32 v[178:179], v[178:179], v[184:185] op_sel_hi:[1,0]
	v_pk_mul_f32 v[180:181], v[180:181], v[184:185] op_sel_hi:[1,0]
	v_cvt_pk_bf16_f32 v26, v174, v175
	v_cvt_pk_bf16_f32 v27, v176, v177
	v_cvt_pk_bf16_f32 v28, v178, v179
	v_cvt_pk_bf16_f32 v29, v180, v181
	v_add_u32_e32 v7, 0x7000, v9
	buffer_store_dwordx4 v[26:29], v7, s[72:75], 0 offen sc1
	s_waitcnt lgkmcnt(4)
	ds_read2st64_b32 v[210:211], v4 offset0:1 offset1:3
	ds_read2st64_b32 v[212:213], v4 offset0:5 offset1:7
	ds_read2st64_b32 v[214:215], v4 offset0:17 offset1:19
	ds_read2st64_b32 v[216:217], v4 offset0:21 offset1:23
	ds_read2st64_b32 v[106:107], v5 offset0:1 offset1:3
	ds_read2st64_b32 v[108:109], v5 offset0:5 offset1:7
	ds_read2st64_b32 v[110:111], v5 offset0:17 offset1:19
	ds_read2st64_b32 v[112:113], v5 offset0:21 offset1:23
	v_pk_mul_f32 v[194:195], v[194:195], v[186:187]
	v_pk_mul_f32 v[196:197], v[196:197], v[188:189]
	v_pk_mul_f32 v[198:199], v[198:199], v[190:191]
	v_pk_mul_f32 v[200:201], v[200:201], v[192:193]
	v_cvt_pk_bf16_f32 v30, v194, v195
	v_cvt_pk_bf16_f32 v31, v196, v197
	v_cvt_pk_bf16_f32 v32, v198, v199
	v_cvt_pk_bf16_f32 v33, v200, v201
	v_add_u32_e32 v6, 0xa000, v9
	buffer_store_dwordx4 v[30:33], v6, s[72:75], 0 offen sc1
	s_waitcnt lgkmcnt(8)
	v_pk_mul_f32 v[202:203], v[202:203], v[186:187]
	v_pk_mul_f32 v[204:205], v[204:205], v[188:189]
	v_pk_mul_f32 v[206:207], v[206:207], v[190:191]
	v_pk_mul_f32 v[208:209], v[208:209], v[192:193]
	v_cvt_pk_bf16_f32 v114, v202, v203
	v_cvt_pk_bf16_f32 v115, v204, v205
	v_cvt_pk_bf16_f32 v116, v206, v207
	v_cvt_pk_bf16_f32 v117, v208, v209
	v_add_u32_e32 v7, 0xb000, v9
	buffer_store_dwordx4 v[114:117], v7, s[72:75], 0 offen sc1
	s_waitcnt lgkmcnt(4)
	v_pk_mul_f32 v[210:211], v[210:211], v[186:187]
	v_pk_mul_f32 v[212:213], v[212:213], v[188:189]
	v_pk_mul_f32 v[214:215], v[214:215], v[190:191]
	v_pk_mul_f32 v[216:217], v[216:217], v[192:193]
	v_cvt_pk_bf16_f32 v118, v210, v211
	v_cvt_pk_bf16_f32 v119, v212, v213
	v_cvt_pk_bf16_f32 v120, v214, v215
	v_cvt_pk_bf16_f32 v121, v216, v217
	v_add_u32_e32 v6, 0xc000, v9
	buffer_store_dwordx4 v[118:121], v6, s[72:75], 0 offen sc1
	s_waitcnt lgkmcnt(0)
	v_pk_mul_f32 v[106:107], v[106:107], v[186:187]
	v_pk_mul_f32 v[108:109], v[108:109], v[188:189]
	v_pk_mul_f32 v[110:111], v[110:111], v[190:191]
	v_pk_mul_f32 v[112:113], v[112:113], v[192:193]
	v_cvt_pk_bf16_f32 v122, v106, v107
	v_cvt_pk_bf16_f32 v123, v108, v109
	v_cvt_pk_bf16_f32 v124, v110, v111
	v_cvt_pk_bf16_f32 v125, v112, v113
	v_add_u32_e32 v7, 0xd000, v9
	buffer_store_dwordx4 v[122:125], v7, s[72:75], 0 offen sc1

.LBB0_238:
	s_setprio 2
	v_lshlrev_b32_e32 v90, 2, v94
	v_readlane_b32 s6, v253, 51
	v_mul_u32_u24_e32 v24, 0x90, v94
	v_and_b32_e32 v2, 32, v1
	v_add_u32_e32 v18, s6, v90
	v_lshl_add_u32 v19, v95, 11, v18
	ds_read2_b32 v[14:15], v19 offset0:32 offset1:96
	ds_read2_b32 v[10:11], v19 offset0:160 offset1:224
	v_readlane_b32 s6, v253, 53
	v_add_u32_e32 v20, 0x80, v19
	v_lshl_add_u32 v18, v89, 8, v18
	v_add3_u32 v26, s6, v24, v2
	ds_read2st64_b32 v[16:17], v20 offset0:4 offset1:5
	ds_read2st64_b32 v[12:13], v20 offset0:6 offset1:7
	ds_read_b128 v[2:5], v26
	ds_read_b128 v[6:9], v26 offset:16
	s_waitcnt lgkmcnt(4)
	v_cvt_pk_bf16_f32 v11, v10, v11
	v_cvt_pk_bf16_f32 v10, v14, v15
	s_waitcnt lgkmcnt(2)
	v_cvt_pk_bf16_f32 v13, v12, v13
	v_cvt_pk_bf16_f32 v12, v16, v17
	s_waitcnt lgkmcnt(0)
	v_cvt_pk_bf16_f32 v9, v8, v9
	v_cvt_pk_bf16_f32 v8, v6, v7
	v_cvt_pk_bf16_f32 v7, v4, v5
	v_cvt_pk_bf16_f32 v6, v2, v3
	ds_read_b32 v91, v18 offset:128
	ds_read2st64_b32 v[22:23], v20 offset0:17 offset1:18
	ds_read2st64_b32 v[30:31], v20 offset0:19 offset1:20
	ds_read2st64_b32 v[32:33], v20 offset0:21 offset1:22
	ds_read_b32 v93, v19 offset:6016
	ds_read_b128 v[18:21], v26 offset:64
	ds_read_b128 v[26:29], v26 offset:80
	v_mfma_f32_32x32x16_bf16 v[2:17], v[10:13], v[6:9], 0
	s_waitcnt lgkmcnt(3)
	v_cvt_pk_bf16_f32 v32, v31, v32
	s_waitcnt lgkmcnt(2)
	v_cvt_pk_bf16_f32 v33, v33, v93
	v_cvt_pk_bf16_f32 v31, v23, v30
	v_cvt_pk_bf16_f32 v30, v91, v22
	s_waitcnt lgkmcnt(1)
	v_cvt_pk_bf16_f32 v21, v20, v21
	v_cvt_pk_bf16_f32 v20, v18, v19
	v_lshlrev_b32_e32 v18, 2, v25
	v_readlane_b32 s6, v253, 52
	s_waitcnt lgkmcnt(0)
	v_cvt_pk_bf16_f32 v23, v28, v29
	v_cvt_pk_bf16_f32 v22, v26, v27
	v_add3_u32 v91, s6, v24, v18
	s_nop 0
	v_mfma_f32_32x32x16_bf16 v[2:17], v[30:33], v[20:23], v[2:17]
	ds_read_b128 v[18:21], v91
	ds_read_b128 v[22:25], v91 offset:32
	s_waitcnt lgkmcnt(0)
	v_cvt_pk_bf16_f32 v25, v24, v25
	v_cvt_pk_bf16_f32 v24, v22, v23
	v_cvt_pk_bf16_f32 v23, v20, v21
	v_cvt_pk_bf16_f32 v22, v18, v19
	s_nop 4
	v_cvt_pk_bf16_f32 v9, v8, v9
	v_cvt_pk_bf16_f32 v8, v6, v7
	v_cvt_pk_bf16_f32 v7, v4, v5
	v_cvt_pk_bf16_f32 v6, v2, v3
	s_nop 1
	v_mfma_f32_32x32x16_bf16 v[18:33], v[22:25], v[6:9], 0
	ds_read_b128 v[2:5], v91 offset:64
	ds_read_b128 v[6:9], v91 offset:96
	s_waitcnt lgkmcnt(0)
	v_cvt_pk_bf16_f32 v9, v8, v9
	v_cvt_pk_bf16_f32 v8, v6, v7
	v_cvt_pk_bf16_f32 v7, v4, v5
	v_cvt_pk_bf16_f32 v6, v2, v3
	v_cvt_pk_bf16_f32 v5, v16, v17
	v_cvt_pk_bf16_f32 v4, v14, v15
	v_cvt_pk_bf16_f32 v3, v12, v13
	v_cvt_pk_bf16_f32 v2, v10, v11
	s_nop 1
	v_mfma_f32_32x32x16_bf16 v[18:33], v[6:9], v[2:5], v[18:33]
	v_add_u32_e32 v2, 0, v90
	v_add_u32_e32 v3, 0x24a00, v2
	ds_read_b32 v3, v3
	v_add_u32_e32 v2, 0x24b00, v2
	ds_read_b32 v2, v2
	v_mul_u32_u24_e32 v5, 0x120, v95
	v_or_b32_e32 v5, v5, v94
	s_waitcnt lgkmcnt(1)
	s_nop 3
	v_lshl_add_u32 v5, v5, 1, 0
	s_waitcnt lgkmcnt(0)
	v_mul_f32_e32 v2, v3, v2
	v_add_u32_e32 v6, 0x19200, v5
	v_add_u32_e32 v5, 0x1b600, v5
	s_cmp_eq_u32 s48, 1
	s_cbranch_scc1 .Lt21_w1
	s_cmp_eq_u32 s48, 2
	s_cbranch_scc1 .Lt21_w2
	s_cmp_eq_u32 s48, 3
	s_cbranch_scc1 .Lt21_w3
	v_mul_f32_e64 v4, v3, -v18
	v_mul_f32_e64 v7, v2, -v18
	v_cvt_pk_bf16_f32 v4, v4, v7
	ds_write_b16 v6, v4
	ds_write_b16_d16_hi v5, v4
	v_mul_f32_e64 v8, v3, -v19
	v_mul_f32_e64 v9, v2, -v19
	v_cvt_pk_bf16_f32 v8, v8, v9
	ds_write_b16 v6, v8 offset:144
	ds_write_b16_d16_hi v5, v8 offset:144
	v_mul_f32_e64 v4, v3, -v20
	v_mul_f32_e64 v7, v2, -v20
	v_cvt_pk_bf16_f32 v4, v4, v7
	ds_write_b16 v6, v4 offset:288
	ds_write_b16_d16_hi v5, v4 offset:288
	v_mul_f32_e64 v8, v3, -v21
	v_mul_f32_e64 v9, v2, -v21
	v_cvt_pk_bf16_f32 v8, v8, v9
	ds_write_b16 v6, v8 offset:432
	ds_write_b16_d16_hi v5, v8 offset:432
	s_branch .Lt21_end
.Lt21_w1:
	v_mul_f32_e64 v4, v3, -v22
	v_mul_f32_e64 v7, v2, -v22
	v_cvt_pk_bf16_f32 v4, v4, v7
	ds_write_b16 v6, v4 offset:1152
	ds_write_b16_d16_hi v5, v4 offset:1152
	v_mul_f32_e64 v8, v3, -v23
	v_mul_f32_e64 v9, v2, -v23
	v_cvt_pk_bf16_f32 v8, v8, v9
	ds_write_b16 v6, v8 offset:1296
	ds_write_b16_d16_hi v5, v8 offset:1296
	v_mul_f32_e64 v4, v3, -v24
	v_mul_f32_e64 v7, v2, -v24
	v_cvt_pk_bf16_f32 v4, v4, v7
	ds_write_b16 v6, v4 offset:1440
	ds_write_b16_d16_hi v5, v4 offset:1440
	v_mul_f32_e64 v8, v3, -v25
	v_mul_f32_e64 v9, v2, -v25
	v_cvt_pk_bf16_f32 v8, v8, v9
	ds_write_b16 v6, v8 offset:1584
	ds_write_b16_d16_hi v5, v8 offset:1584
	s_branch .Lt21_end
.Lt21_w2:
	v_mul_f32_e64 v4, v3, -v26
	v_mul_f32_e64 v7, v2, -v26
	v_cvt_pk_bf16_f32 v4, v4, v7
	ds_write_b16 v6, v4 offset:2304
	ds_write_b16_d16_hi v5, v4 offset:2304
	v_mul_f32_e64 v8, v3, -v27
	v_mul_f32_e64 v9, v2, -v27
	v_cvt_pk_bf16_f32 v8, v8, v9
	ds_write_b16 v6, v8 offset:2448
	ds_write_b16_d16_hi v5, v8 offset:2448
	v_mul_f32_e64 v4, v3, -v28
	v_mul_f32_e64 v7, v2, -v28
	v_cvt_pk_bf16_f32 v4, v4, v7
	ds_write_b16 v6, v4 offset:2592
	ds_write_b16_d16_hi v5, v4 offset:2592
	v_mul_f32_e64 v8, v3, -v29
	v_mul_f32_e64 v9, v2, -v29
	v_cvt_pk_bf16_f32 v8, v8, v9
	ds_write_b16 v6, v8 offset:2736
	ds_write_b16_d16_hi v5, v8 offset:2736
	s_branch .Lt21_end
.Lt21_w3:
	v_mul_f32_e64 v4, v3, -v30
	v_mul_f32_e64 v7, v2, -v30
	v_cvt_pk_bf16_f32 v4, v4, v7
	ds_write_b16 v6, v4 offset:3456
	ds_write_b16_d16_hi v5, v4 offset:3456
	v_mul_f32_e64 v8, v3, -v31
	v_mul_f32_e64 v9, v2, -v31
	v_cvt_pk_bf16_f32 v8, v8, v9
	ds_write_b16 v6, v8 offset:3600
	ds_write_b16_d16_hi v5, v8 offset:3600
	v_mul_f32_e64 v4, v3, -v32
	v_mul_f32_e64 v7, v2, -v32
	v_cvt_pk_bf16_f32 v4, v4, v7
	ds_write_b16 v6, v4 offset:3744
	ds_write_b16_d16_hi v5, v4 offset:3744
	v_mul_f32_e64 v8, v3, -v33
	v_mul_f32_e64 v9, v2, -v33
	v_cvt_pk_bf16_f32 v8, v8, v9
	ds_write_b16 v6, v8 offset:3888
	ds_write_b16_d16_hi v5, v8 offset:3888
.Lt21_end:
	v_mov_b32_e32 v18, v89
	s_setprio 0
